# baseline (speedup 1.0000x reference)
; template <class Epi>
; DEV void gemm_phase(LAS unsigned char* lds, const Gemm g, const StaticOrder& S, const Epi& E) {
;     ...
;         const bool has_next = S.next(ui + 1, nxt);
;         const char* nA = has_next ? (const char*)g.A + (size_t)nxt.pm * tstep : cA; const char* nB = has_next ? (const char*)g.Bt + (size_t)nxt.pn * tstep : cB;
;         for (int t = 0; t < nt; t += 2) {
;             const bool last = (t == nt - 2);
;             const char* a1 = cA + (size_t)(t + 1) * kstep;
;             const char* a2 = last ? nA : cA + (size_t)(t + 2) * kstep; const char* b2 = last ? nB : cB + (size_t)(t + 2) * kstep;
;     ...
; #pragma unroll
;         for (int a = 0; a < 2; ++a)
; #pragma unroll
;             for (int b = 0; b < 2; ++b)
; #pragma unroll
;                 for (int m = 0; m < 4; ++m)
; #pragma unroll
;                     for (int n = 0; n < 2; ++n) acc[a][b][m][n] = (f32x4){0.f, 0.f, 0.f, 0.f};
;         cur = nxt; cA = nA; cB = nB; ++ui;
.LBB0_151:
	v_mov_b64_e32 v[0:1], 0x140
	s_ashr_i32 s11, s10, 31
	v_cmp_lt_i64_e32 vcc, s[12:13], v[0:1]
	s_lshl_b64 s[12:13], s[10:11], 20
	v_readlane_b32 s14, v250, 9
	v_readlane_b32 s15, v250, 10
	s_add_u32 s12, s14, s12
	s_addc_u32 s13, s15, s13
	s_and_b64 s[14:15], vcc, exec
	s_cselect_b32 s5, s13, s19
	s_cselect_b32 s11, s12, s18
	s_ashr_i32 s9, s8, 31
	s_lshl_b64 s[14:15], s[8:9], 20
	v_readlane_b32 s22, v250, 49
	v_readlane_b32 s23, v250, 50
	s_add_u32 s14, s22, s14
	s_addc_u32 s15, s23, s15
	s_and_b64 s[22:23], vcc, exec
	s_cselect_b32 s9, s15, s21
	s_cselect_b32 s37, s14, s20
	s_add_u32 s18, s18, 0x80080
	s_addc_u32 s19, s19, 0
	s_add_u32 s38, s20, 0x100
	s_addc_u32 s39, s21, 0
	s_mov_b32 s40, -2
	v_mov_b64_e32 v[0:1], 0
	v_mov_b64_e32 v[2:3], 0
	v_mov_b64_e32 v[4:5], 0
	v_mov_b64_e32 v[6:7], 0
	v_mov_b64_e32 v[8:9], 0
	v_mov_b64_e32 v[10:11], 0
	v_mov_b64_e32 v[12:13], 0
	v_mov_b64_e32 v[14:15], 0
	v_mov_b64_e32 v[16:17], 0
	v_mov_b64_e32 v[18:19], 0
	v_mov_b64_e32 v[20:21], 0
	v_mov_b64_e32 v[22:23], 0
	v_mov_b64_e32 v[24:25], 0
	v_mov_b64_e32 v[26:27], 0
	v_mov_b64_e32 v[28:29], 0
	v_mov_b64_e32 v[30:31], 0
	v_mov_b64_e32 v[32:33], 0
	v_mov_b64_e32 v[34:35], 0
	v_mov_b64_e32 v[36:37], 0
	v_mov_b64_e32 v[38:39], 0
	v_mov_b64_e32 v[40:41], 0
	v_mov_b64_e32 v[42:43], 0
	v_mov_b64_e32 v[44:45], 0
	v_mov_b64_e32 v[46:47], 0
	v_mov_b64_e32 v[48:49], 0
	v_mov_b64_e32 v[50:51], 0
	v_mov_b64_e32 v[52:53], 0
	v_mov_b64_e32 v[54:55], 0
	v_mov_b64_e32 v[56:57], 0
	v_mov_b64_e32 v[58:59], 0
	v_mov_b64_e32 v[60:61], 0
	v_mov_b64_e32 v[62:63], 0
	v_mov_b64_e32 v[64:65], 0
	v_mov_b64_e32 v[66:67], 0
	v_mov_b64_e32 v[68:69], 0
	v_mov_b64_e32 v[70:71], 0
	v_mov_b64_e32 v[72:73], 0
	v_mov_b64_e32 v[74:75], 0
	v_mov_b64_e32 v[76:77], 0
	v_mov_b64_e32 v[78:79], 0
	v_mov_b64_e32 v[80:81], 0
	v_mov_b64_e32 v[82:83], 0
	v_mov_b64_e32 v[84:85], 0
	v_mov_b64_e32 v[86:87], 0
	v_mov_b64_e32 v[88:89], 0
	v_mov_b64_e32 v[90:91], 0
	v_mov_b64_e32 v[92:93], 0
	v_mov_b64_e32 v[94:95], 0
	v_mov_b64_e32 v[96:97], 0
	v_mov_b64_e32 v[98:99], 0
	v_mov_b64_e32 v[100:101], 0
	v_mov_b64_e32 v[102:103], 0
	v_mov_b64_e32 v[104:105], 0
	v_mov_b64_e32 v[106:107], 0
	v_mov_b64_e32 v[108:109], 0
	v_mov_b64_e32 v[110:111], 0
	v_mov_b64_e32 v[112:113], 0
	v_mov_b64_e32 v[114:115], 0
	v_mov_b64_e32 v[116:117], 0
	v_mov_b64_e32 v[118:119], 0
	v_mov_b64_e32 v[120:121], 0
	v_mov_b64_e32 v[122:123], 0
	v_mov_b64_e32 v[124:125], 0
	v_mov_b64_e32 v[126:127], 0

; template <class Epi>
; DEV void gemm_phase(LAS unsigned char* lds, const Gemm g, const StaticOrder& S, const Epi& E) {
;     ...
;         const bool has_next = S.next(ui + 1, nxt);
;         const char* nA = has_next ? (const char*)g.A + (size_t)nxt.pm * tstep : cA; const char* nB = has_next ? (const char*)g.Bt + (size_t)nxt.pn * tstep : cB;
;         for (int t = 0; t < nt; t += 2) {
;             const bool last = (t == nt - 2);
;             const char* a1 = cA + (size_t)(t + 1) * kstep;
;             const char* a2 = last ? nA : cA + (size_t)(t + 2) * kstep; const char* b2 = last ? nB : cB + (size_t)(t + 2) * kstep;
;     ...
; #pragma unroll
;         for (int a = 0; a < 2; ++a)
; #pragma unroll
;             for (int b = 0; b < 2; ++b)
; #pragma unroll
;                 for (int m = 0; m < 4; ++m)
; #pragma unroll
;                     for (int n = 0; n < 2; ++n) acc[a][b][m][n] = (f32x4){0.f, 0.f, 0.f, 0.f};
;         cur = nxt; cA = nA; cB = nB; ++ui;
.LBB0_343:
	s_ashr_i32 s13, s12, 31
	v_cmp_lt_i64_e64 s[22:23], s[14:15], 64
	s_lshl_b64 s[14:15], s[12:13], 20
	v_readlane_b32 s16, v250, 9
	v_readlane_b32 s17, v250, 10
	s_add_u32 s14, s16, s14
	s_addc_u32 s15, s17, s15
	s_and_b64 s[16:17], s[22:23], exec
	s_cselect_b32 s1, s15, s19
	s_cselect_b32 s13, s14, s18
	s_ashr_i32 s11, s10, 31
	s_lshl_b64 s[16:17], s[10:11], 20
	s_add_u32 s16, s27, s16
	s_addc_u32 s17, s28, s17
	s_and_b64 s[22:23], s[22:23], exec
	s_cselect_b32 s11, s17, s21
	s_cselect_b32 s41, s16, s20
	s_add_u32 s18, s18, 0x80080
	s_addc_u32 s19, s19, 0
	s_add_u32 s42, s20, 0x100
	s_addc_u32 s43, s21, 0
	s_mov_b32 s44, -2
	v_mov_b64_e32 v[0:1], 0
	v_mov_b64_e32 v[2:3], 0
	v_mov_b64_e32 v[4:5], 0
	v_mov_b64_e32 v[6:7], 0
	v_mov_b64_e32 v[8:9], 0
	v_mov_b64_e32 v[10:11], 0
	v_mov_b64_e32 v[12:13], 0
	v_mov_b64_e32 v[14:15], 0
	v_mov_b64_e32 v[16:17], 0
	v_mov_b64_e32 v[18:19], 0
	v_mov_b64_e32 v[20:21], 0
	v_mov_b64_e32 v[22:23], 0
	v_mov_b64_e32 v[24:25], 0
	v_mov_b64_e32 v[26:27], 0
	v_mov_b64_e32 v[28:29], 0
	v_mov_b64_e32 v[30:31], 0
	v_mov_b64_e32 v[32:33], 0
	v_mov_b64_e32 v[34:35], 0
	v_mov_b64_e32 v[36:37], 0
	v_mov_b64_e32 v[38:39], 0
	v_mov_b64_e32 v[40:41], 0
	v_mov_b64_e32 v[42:43], 0
	v_mov_b64_e32 v[44:45], 0
	v_mov_b64_e32 v[46:47], 0
	v_mov_b64_e32 v[48:49], 0
	v_mov_b64_e32 v[50:51], 0
	v_mov_b64_e32 v[52:53], 0
	v_mov_b64_e32 v[54:55], 0
	v_mov_b64_e32 v[56:57], 0
	v_mov_b64_e32 v[58:59], 0
	v_mov_b64_e32 v[60:61], 0
	v_mov_b64_e32 v[62:63], 0
	v_mov_b64_e32 v[64:65], 0
	v_mov_b64_e32 v[66:67], 0
	v_mov_b64_e32 v[68:69], 0
	v_mov_b64_e32 v[70:71], 0
	v_mov_b64_e32 v[72:73], 0
	v_mov_b64_e32 v[74:75], 0
	v_mov_b64_e32 v[76:77], 0
	v_mov_b64_e32 v[78:79], 0
	v_mov_b64_e32 v[80:81], 0
	v_mov_b64_e32 v[82:83], 0
	v_mov_b64_e32 v[84:85], 0
	v_mov_b64_e32 v[86:87], 0
	v_mov_b64_e32 v[88:89], 0
	v_mov_b64_e32 v[90:91], 0
	v_mov_b64_e32 v[92:93], 0
	v_mov_b64_e32 v[94:95], 0
	v_mov_b64_e32 v[96:97], 0
	v_mov_b64_e32 v[98:99], 0
	v_mov_b64_e32 v[100:101], 0
	v_mov_b64_e32 v[102:103], 0
	v_mov_b64_e32 v[104:105], 0
	v_mov_b64_e32 v[106:107], 0
	v_mov_b64_e32 v[108:109], 0
	v_mov_b64_e32 v[110:111], 0
	v_mov_b64_e32 v[112:113], 0
	v_mov_b64_e32 v[114:115], 0
	v_mov_b64_e32 v[116:117], 0
	v_mov_b64_e32 v[118:119], 0
	v_mov_b64_e32 v[120:121], 0
	v_mov_b64_e32 v[122:123], 0
	v_mov_b64_e32 v[124:125], 0
	v_mov_b64_e32 v[126:127], 0

; template <class Epi>
; DEV void gemm_phase(LAS unsigned char* lds, const Gemm g, const StaticOrder& S, const Epi& E) {
;     ...
;         const bool has_next = S.next(ui + 1, nxt);
;         const char* nA = has_next ? (const char*)g.A + (size_t)nxt.pm * tstep : cA; const char* nB = has_next ? (const char*)g.Bt + (size_t)nxt.pn * tstep : cB;
;         for (int t = 0; t < nt; t += 2) {
;             const bool last = (t == nt - 2);
;             const char* a1 = cA + (size_t)(t + 1) * kstep;
;             const char* a2 = last ? nA : cA + (size_t)(t + 2) * kstep; const char* b2 = last ? nB : cB + (size_t)(t + 2) * kstep;
;     ...
; #pragma unroll
;         for (int a = 0; a < 2; ++a)
; #pragma unroll
;             for (int b = 0; b < 2; ++b)
; #pragma unroll
;                 for (int m = 0; m < 4; ++m)
; #pragma unroll
;                     for (int n = 0; n < 2; ++n) acc[a][b][m][n] = (f32x4){0.f, 0.f, 0.f, 0.f};
;         cur = nxt; cA = nA; cB = nB; ++ui;
.LBB0_361:
	s_ashr_i32 s19, s18, 31
	v_cmp_lt_i64_e64 s[28:29], s[20:21], 4
	s_lshl_b64 s[20:21], s[18:19], 20
	s_add_u32 s20, s37, s20
	s_addc_u32 s21, s38, s21
	s_and_b64 s[22:23], s[28:29], exec
	s_cselect_b32 s19, s21, s25
	s_cselect_b32 s51, s20, s24
	s_ashr_i32 s17, s16, 31
	s_lshl_b64 s[22:23], s[16:17], 20
	s_add_u32 s22, s39, s22
	s_addc_u32 s23, s40, s23
	s_and_b64 s[28:29], s[28:29], exec
	s_cselect_b32 s17, s23, s27
	s_cselect_b32 s52, s22, s26
	s_add_u32 s24, s24, 0x80080
	s_addc_u32 s25, s25, 0
	s_add_u32 s53, s26, 0x100
	s_addc_u32 s54, s27, 0
	s_mov_b32 s55, -2
	v_mov_b64_e32 v[0:1], 0
	v_mov_b64_e32 v[2:3], 0
	v_mov_b64_e32 v[4:5], 0
	v_mov_b64_e32 v[6:7], 0
	v_mov_b64_e32 v[8:9], 0
	v_mov_b64_e32 v[10:11], 0
	v_mov_b64_e32 v[12:13], 0
	v_mov_b64_e32 v[14:15], 0
	v_mov_b64_e32 v[16:17], 0
	v_mov_b64_e32 v[18:19], 0
	v_mov_b64_e32 v[20:21], 0
	v_mov_b64_e32 v[22:23], 0
	v_mov_b64_e32 v[24:25], 0
	v_mov_b64_e32 v[26:27], 0
	v_mov_b64_e32 v[28:29], 0
	v_mov_b64_e32 v[30:31], 0
	v_mov_b64_e32 v[32:33], 0
	v_mov_b64_e32 v[34:35], 0
	v_mov_b64_e32 v[36:37], 0
	v_mov_b64_e32 v[38:39], 0
	v_mov_b64_e32 v[40:41], 0
	v_mov_b64_e32 v[42:43], 0
	v_mov_b64_e32 v[44:45], 0
	v_mov_b64_e32 v[46:47], 0
	v_mov_b64_e32 v[48:49], 0
	v_mov_b64_e32 v[50:51], 0
	v_mov_b64_e32 v[52:53], 0
	v_mov_b64_e32 v[54:55], 0
	v_mov_b64_e32 v[56:57], 0
	v_mov_b64_e32 v[58:59], 0
	v_mov_b64_e32 v[60:61], 0
	v_mov_b64_e32 v[62:63], 0
	v_mov_b64_e32 v[64:65], 0
	v_mov_b64_e32 v[66:67], 0
	v_mov_b64_e32 v[68:69], 0
	v_mov_b64_e32 v[70:71], 0
	v_mov_b64_e32 v[72:73], 0
	v_mov_b64_e32 v[74:75], 0
	v_mov_b64_e32 v[76:77], 0
	v_mov_b64_e32 v[78:79], 0
	v_mov_b64_e32 v[80:81], 0
	v_mov_b64_e32 v[82:83], 0
	v_mov_b64_e32 v[84:85], 0
	v_mov_b64_e32 v[86:87], 0
	v_mov_b64_e32 v[88:89], 0
	v_mov_b64_e32 v[90:91], 0
	v_mov_b64_e32 v[92:93], 0
	v_mov_b64_e32 v[94:95], 0
	v_mov_b64_e32 v[96:97], 0
	v_mov_b64_e32 v[98:99], 0
	v_mov_b64_e32 v[100:101], 0
	v_mov_b64_e32 v[102:103], 0
	v_mov_b64_e32 v[104:105], 0
	v_mov_b64_e32 v[106:107], 0
	v_mov_b64_e32 v[108:109], 0
	v_mov_b64_e32 v[110:111], 0
	v_mov_b64_e32 v[112:113], 0
	v_mov_b64_e32 v[114:115], 0
	v_mov_b64_e32 v[116:117], 0
	v_mov_b64_e32 v[118:119], 0
	v_mov_b64_e32 v[120:121], 0
	v_mov_b64_e32 v[122:123], 0
	v_mov_b64_e32 v[124:125], 0
	v_mov_b64_e32 v[126:127], 0

; template <class Epi>
; DEV void gemm_phase(LAS unsigned char* lds, const Gemm g, const StaticOrder& S, const Epi& E) {
;     ...
;         const bool has_next = S.next(ui + 1, nxt);
;         const char* nA = has_next ? (const char*)g.A + (size_t)nxt.pm * tstep : cA; const char* nB = has_next ? (const char*)g.Bt + (size_t)nxt.pn * tstep : cB;
;         for (int t = 0; t < nt; t += 2) {
;             const bool last = (t == nt - 2);
;             const char* a1 = cA + (size_t)(t + 1) * kstep;
;             const char* a2 = last ? nA : cA + (size_t)(t + 2) * kstep; const char* b2 = last ? nB : cB + (size_t)(t + 2) * kstep;
;     ...
; #pragma unroll
;         for (int a = 0; a < 2; ++a)
; #pragma unroll
;             for (int b = 0; b < 2; ++b)
; #pragma unroll
;                 for (int m = 0; m < 4; ++m)
; #pragma unroll
;                     for (int n = 0; n < 2; ++n) acc[a][b][m][n] = (f32x4){0.f, 0.f, 0.f, 0.f};
;         cur = nxt; cA = nA; cB = nB; ++ui;
.LBB0_587:
	v_mov_b64_e32 v[0:1], 0x4a0
	s_ashr_i32 s9, s8, 31
	v_cmp_lt_i64_e32 vcc, s[10:11], v[0:1]
	s_lshl_b64 s[10:11], s[8:9], 20
	v_readlane_b32 s12, v250, 9
	v_readlane_b32 s13, v250, 10
	s_add_u32 s10, s12, s10
	s_addc_u32 s11, s13, s11
	s_and_b64 s[12:13], vcc, exec
	s_cselect_b32 s1, s11, s15
	s_cselect_b32 s9, s10, s14
	s_ashr_i32 s7, s6, 31
	s_lshl_b64 s[12:13], s[6:7], 20
	v_readlane_b32 s18, v251, 41
	v_readlane_b32 s19, v251, 42
	s_add_u32 s12, s18, s12
	s_addc_u32 s13, s19, s13
	s_and_b64 s[18:19], vcc, exec
	s_cselect_b32 s7, s13, s17
	s_cselect_b32 s35, s12, s16
	s_add_u32 s14, s14, 0x80080
	s_addc_u32 s15, s15, 0
	s_add_u32 s36, s16, 0x100
	s_addc_u32 s37, s17, 0
	s_mov_b32 s40, -2
	v_mov_b64_e32 v[0:1], 0
	v_mov_b64_e32 v[2:3], 0
	v_mov_b64_e32 v[4:5], 0
	v_mov_b64_e32 v[6:7], 0
	v_mov_b64_e32 v[8:9], 0
	v_mov_b64_e32 v[10:11], 0
	v_mov_b64_e32 v[12:13], 0
	v_mov_b64_e32 v[14:15], 0
	v_mov_b64_e32 v[16:17], 0
	v_mov_b64_e32 v[18:19], 0
	v_mov_b64_e32 v[20:21], 0
	v_mov_b64_e32 v[22:23], 0
	v_mov_b64_e32 v[24:25], 0
	v_mov_b64_e32 v[26:27], 0
	v_mov_b64_e32 v[28:29], 0
	v_mov_b64_e32 v[30:31], 0
	v_mov_b64_e32 v[32:33], 0
	v_mov_b64_e32 v[34:35], 0
	v_mov_b64_e32 v[36:37], 0
	v_mov_b64_e32 v[38:39], 0
	v_mov_b64_e32 v[40:41], 0
	v_mov_b64_e32 v[42:43], 0
	v_mov_b64_e32 v[44:45], 0
	v_mov_b64_e32 v[46:47], 0
	v_mov_b64_e32 v[48:49], 0
	v_mov_b64_e32 v[50:51], 0
	v_mov_b64_e32 v[52:53], 0
	v_mov_b64_e32 v[54:55], 0
	v_mov_b64_e32 v[56:57], 0
	v_mov_b64_e32 v[58:59], 0
	v_mov_b64_e32 v[60:61], 0
	v_mov_b64_e32 v[62:63], 0
	v_mov_b64_e32 v[64:65], 0
	v_mov_b64_e32 v[66:67], 0
	v_mov_b64_e32 v[68:69], 0
	v_mov_b64_e32 v[70:71], 0
	v_mov_b64_e32 v[72:73], 0
	v_mov_b64_e32 v[74:75], 0
	v_mov_b64_e32 v[76:77], 0
	v_mov_b64_e32 v[78:79], 0
	v_mov_b64_e32 v[80:81], 0
	v_mov_b64_e32 v[82:83], 0
	v_mov_b64_e32 v[84:85], 0
	v_mov_b64_e32 v[86:87], 0
	v_mov_b64_e32 v[88:89], 0
	v_mov_b64_e32 v[90:91], 0
	v_mov_b64_e32 v[92:93], 0
	v_mov_b64_e32 v[94:95], 0
	v_mov_b64_e32 v[96:97], 0
	v_mov_b64_e32 v[98:99], 0
	v_mov_b64_e32 v[100:101], 0
	v_mov_b64_e32 v[102:103], 0
	v_mov_b64_e32 v[104:105], 0
	v_mov_b64_e32 v[106:107], 0
	v_mov_b64_e32 v[108:109], 0
	v_mov_b64_e32 v[110:111], 0
	v_mov_b64_e32 v[112:113], 0
	v_mov_b64_e32 v[114:115], 0
	v_mov_b64_e32 v[116:117], 0
	v_mov_b64_e32 v[118:119], 0
	v_mov_b64_e32 v[120:121], 0
	v_mov_b64_e32 v[122:123], 0
	v_mov_b64_e32 v[124:125], 0
	v_mov_b64_e32 v[126:127], 0

; template <class Epi>
; DEV void gemm_phase(LAS unsigned char* lds, const Gemm g, const StaticOrder& S, const Epi& E) {
;     ...
;         const bool has_next = S.next(ui + 1, nxt);
;         const char* nA = has_next ? (const char*)g.A + (size_t)nxt.pm * tstep : cA; const char* nB = has_next ? (const char*)g.Bt + (size_t)nxt.pn * tstep : cB;
;         for (int t = 0; t < nt; t += 2) {
;             const bool last = (t == nt - 2);
;             const char* a1 = cA + (size_t)(t + 1) * kstep;
;             const char* a2 = last ? nA : cA + (size_t)(t + 2) * kstep; const char* b2 = last ? nB : cB + (size_t)(t + 2) * kstep;
;     ...
; #pragma unroll
;         for (int a = 0; a < 2; ++a)
; #pragma unroll
;             for (int b = 0; b < 2; ++b)
; #pragma unroll
;                 for (int m = 0; m < 4; ++m)
; #pragma unroll
;                     for (int n = 0; n < 2; ++n) acc[a][b][m][n] = (f32x4){0.f, 0.f, 0.f, 0.f};
;         cur = nxt; cA = nA; cB = nB; ++ui;
.LBB0_754:
	s_ashr_i32 s15, s14, 31
	v_cmp_lt_i64_e32 vcc, s[16:17], v[168:169]
	s_lshl_b64 s[16:17], s[14:15], 20
	v_readlane_b32 s18, v250, 9
	v_readlane_b32 s19, v250, 10
	s_add_u32 s16, s18, s16
	s_addc_u32 s17, s19, s17
	s_and_b64 s[18:19], vcc, exec
	s_cselect_b32 s5, s17, s21
	s_cselect_b32 s15, s16, s20
	s_ashr_i32 s11, s10, 31
	s_lshl_b64 s[18:19], s[10:11], 20
	s_add_u32 s18, s28, s18
	s_addc_u32 s19, s29, s19
	s_and_b64 s[24:25], vcc, exec
	s_cselect_b32 s11, s19, s23
	s_cselect_b32 s43, s18, s22
	s_add_u32 s20, s20, 0x80080
	s_addc_u32 s21, s21, 0
	s_add_u32 s44, s22, 0x100
	s_addc_u32 s45, s23, 0
	s_mov_b32 s46, -2
	v_mov_b64_e32 v[0:1], 0
	v_mov_b64_e32 v[2:3], 0
	v_mov_b64_e32 v[4:5], 0
	v_mov_b64_e32 v[6:7], 0
	v_mov_b64_e32 v[8:9], 0
	v_mov_b64_e32 v[10:11], 0
	v_mov_b64_e32 v[12:13], 0
	v_mov_b64_e32 v[14:15], 0
	v_mov_b64_e32 v[16:17], 0
	v_mov_b64_e32 v[18:19], 0
	v_mov_b64_e32 v[20:21], 0
	v_mov_b64_e32 v[22:23], 0
	v_mov_b64_e32 v[24:25], 0
	v_mov_b64_e32 v[26:27], 0
	v_mov_b64_e32 v[28:29], 0
	v_mov_b64_e32 v[30:31], 0
	v_mov_b64_e32 v[32:33], 0
	v_mov_b64_e32 v[34:35], 0
	v_mov_b64_e32 v[36:37], 0
	v_mov_b64_e32 v[38:39], 0
	v_mov_b64_e32 v[40:41], 0
	v_mov_b64_e32 v[42:43], 0
	v_mov_b64_e32 v[44:45], 0
	v_mov_b64_e32 v[46:47], 0
	v_mov_b64_e32 v[48:49], 0
	v_mov_b64_e32 v[50:51], 0
	v_mov_b64_e32 v[52:53], 0
	v_mov_b64_e32 v[54:55], 0
	v_mov_b64_e32 v[56:57], 0
	v_mov_b64_e32 v[58:59], 0
	v_mov_b64_e32 v[60:61], 0
	v_mov_b64_e32 v[62:63], 0
	v_mov_b64_e32 v[64:65], 0
	v_mov_b64_e32 v[66:67], 0
	v_mov_b64_e32 v[68:69], 0
	v_mov_b64_e32 v[70:71], 0
	v_mov_b64_e32 v[72:73], 0
	v_mov_b64_e32 v[74:75], 0
	v_mov_b64_e32 v[76:77], 0
	v_mov_b64_e32 v[78:79], 0
	v_mov_b64_e32 v[80:81], 0
	v_mov_b64_e32 v[82:83], 0
	v_mov_b64_e32 v[84:85], 0
	v_mov_b64_e32 v[86:87], 0
	v_mov_b64_e32 v[88:89], 0
	v_mov_b64_e32 v[90:91], 0
	v_mov_b64_e32 v[92:93], 0
	v_mov_b64_e32 v[94:95], 0
	v_mov_b64_e32 v[96:97], 0
	v_mov_b64_e32 v[98:99], 0
	v_mov_b64_e32 v[100:101], 0
	v_mov_b64_e32 v[102:103], 0
	v_mov_b64_e32 v[104:105], 0
	v_mov_b64_e32 v[106:107], 0
	v_mov_b64_e32 v[108:109], 0
	v_mov_b64_e32 v[110:111], 0
	v_mov_b64_e32 v[112:113], 0
	v_mov_b64_e32 v[114:115], 0
	v_mov_b64_e32 v[116:117], 0
	v_mov_b64_e32 v[118:119], 0
	v_mov_b64_e32 v[120:121], 0
	v_mov_b64_e32 v[122:123], 0
	v_mov_b64_e32 v[124:125], 0
	v_mov_b64_e32 v[126:127], 0
